# GEMM tile order: 16 row tiles per column-major group instead of 8
# baseline (speedup 1.0000x reference)
;     __device__ bool next(int i, Unit& u) const {
;         const long L = (long)i * G + c; if (L >= nwg) return false;
;         int wgid = (int)L; { const int q = nwg / NXCD, r = nwg % NXCD, xcd = wgid % NXCD, off = wgid / NXCD; wgid = (xcd < r ? xcd * (q + 1) : r * (q + 1) + (xcd - r) * q) + off; }
;         const int nig = WGM * nN, gid = wgid / nig, fm = gid * WGM, gsz = (nM - fm) < WGM ? (nM - fm) : WGM;
;         u.pm = fm + ((wgid % nig) % gsz); u.pn = (wgid % nig) / gsz; return true;
;     }
.LBB0_254:
	s_lshl_b32 s4, s18, 4
	v_cvt_f32_u32_e32 v0, s4
	s_ashr_i32 s5, s8, 3
	s_sub_i32 s8, 0, s4
	s_add_i32 s5, s13, s5
	v_rcp_iflag_f32_e32 v0, v0
	s_abs_i32 s14, s5
	s_ashr_i32 s13, s5, 31
	v_mul_f32_e32 v0, 0x4f7ffffe, v0
	v_cvt_u32_f32_e32 v0, v0
	s_nop 0
	v_readfirstlane_b32 s15, v0
	s_mul_i32 s8, s8, s15
	s_mul_hi_u32 s8, s15, s8
	s_add_i32 s15, s15, s8
	s_mul_hi_u32 s8, s14, s15
	s_mul_i32 s15, s8, s4
	s_sub_i32 s14, s14, s15
	s_add_i32 s19, s8, 1
	s_sub_i32 s15, s14, s4
	s_cmp_ge_u32 s14, s4
	s_cselect_b32 s8, s19, s8
	s_cselect_b32 s14, s15, s14
	s_add_i32 s15, s8, 1
	s_cmp_ge_u32 s14, s4
	s_cselect_b32 s8, s15, s8
	s_xor_b32 s8, s8, s13
	s_sub_i32 s8, s8, s13
	s_lshl_b32 s13, s8, 4
	s_mul_i32 s8, s8, s4
	s_sub_i32 s4, s96, s13
	s_min_i32 s14, s4, 16
	s_sext_i32_i16 s4, s14
	v_cvt_f32_i32_e32 v0, s4
	s_sub_i32 s8, s5, s8
	s_sext_i32_i16 s5, s8
	v_cvt_f32_i32_e32 v2, s5
	v_rcp_iflag_f32_e32 v3, v0
	s_xor_b32 s4, s5, s4
	s_ashr_i32 s4, s4, 30
	s_or_b32 s15, s4, 1
	v_mul_f32_e32 v3, v2, v3
	v_trunc_f32_e32 v3, v3
	v_fma_f32 v2, -v3, v0, v2
	v_cvt_i32_f32_e32 v3, v3
	v_cmp_ge_f32_e64 s[4:5], |v2|, |v0|
	s_and_b64 s[4:5], s[4:5], exec
	s_cselect_b32 s4, s15, 0
	v_readfirstlane_b32 s5, v3
	s_add_i32 s4, s5, s4
	s_sext_i32_i16 s71, s4
	s_mul_i32 s4, s4, s14
	s_sub_i32 s4, s8, s4
	s_sext_i32_i16 s4, s4
	s_add_i32 s63, s13, s4

; __device__ __forceinline__ int opaque_tid(int wv) { int t = wv * 64 + (int)__builtin_amdgcn_mbcnt_hi(~0u, __builtin_amdgcn_mbcnt_lo(~0u, 0u)); asm volatile("" : "+v"(t)); return t; }
; #define PG8_STAGE(bufoff, gbase, voff) do { _Pragma("unroll") for (int _i = 0; _i < 2; ++_i) \
;         __builtin_amdgcn_global_load_lds((const unsigned*)((const char*)(gbase) + (voff)[_i]), (LAS unsigned*)(lds + (bufoff) + ldsw + _i * 8192), 16, 0, 0); } while (0)
; #define PG8_WAIT_V(n) asm volatile("s_waitcnt vmcnt(" #n ")" ::: "memory")
; #define PG8_BAR __builtin_amdgcn_s_barrier()
; template <class EpiT>
; __device__ __forceinline__ void gemm_phase(LAS unsigned char* lds, const Gemm g, const StaticOrder& S, const EpiT& E, int wv) {
;     const int tid = opaque_tid(wv), wid = __builtin_amdgcn_readfirstlane(tid >> 6), lane = tid & 63, wr = wid >> 2, wc = wid & 3, fr = lane & 15, fq = lane >> 4;
;     int K = g.K; asm volatile("" : "+s"(K)); const int nt = K / BK;
;     unsigned voffA[2], voffB[2];
; #pragma unroll
;     for (int i = 0; i < 2; ++i) { int R, C; stage_rc(tid * 16 + i * 8192, R, C); const int Rb = (R & ~31) + perm32(R & 31);
;         voffA[i] = (unsigned)(R * g.lda + C) * 2u; voffB[i] = (unsigned)(Rb * g.ldb + C) * 2u; }
;     const size_t kstep = (size_t)(BK * 2);
;     const size_t hA = (size_t)HALF * g.lda * 2, hB = (size_t)HALF * g.ldb * 2;
;     const size_t tA = 2 * hA, tB = 2 * hB;
;     const unsigned ldsw = (unsigned)wid * 1024u;
;     const int aoff = lds_byte(wr * 64 + fr, fq * 8), boff = lds_byte(wc * 32 + fr, fq * 8);
;     ...
;     const char* cA = (const char*)g.A + (size_t)cur.pm * tA + (size_t)cur.pn * g.apn * 2; const char* cB = (const char*)g.Bt + (size_t)cur.pn * tB;
;     PG8_STAGE(PG8_SB(0, 0), cB, voffB); PG8_STAGE(PG8_SB(0, 1), cB + hB, voffB); PG8_STAGE(PG8_SA(0, 0), cA, voffA); PG8_STAGE(PG8_SA(0, 1), cA + hA, voffA);
;     if (wr == 1) PG8_BAR;
;     PG8_WAIT_V(2); PG8_BAR;
;     PG8_STAGE(PG8_SB(1, 0), cB + kstep, voffB); PG8_STAGE(PG8_SA(1, 0), cA + kstep, voffA); PG8_STAGE(PG8_SB(1, 1), cB + hB + kstep, voffB);
;     PG8_WAIT_V(6); PG8_BAR;
.LBB0_258:
	s_add_i32 m0, s14, 0x18000
	v_lshl_add_u64 v[4:5], v[4:5], 0, s[10:11]
	s_waitcnt vmcnt(2)
	s_barrier
	global_load_lds_dwordx4 v[4:5], off
	v_lshl_add_u64 v[4:5], v[6:7], 0, s[10:11]
	s_add_i32 m0, s14, 0x1a000
	s_add_i32 s72, s14, 0x8000
	global_load_lds_dwordx4 v[4:5], off
	v_lshl_add_u64 v[4:5], v[12:13], 0, s[10:11]
	s_mov_b32 m0, s72
	s_add_i32 s73, s14, 0xa000
	global_load_lds_dwordx4 v[4:5], off
	v_lshl_add_u64 v[4:5], v[18:19], 0, s[10:11]
	s_mov_b32 m0, s73
	s_and_b32 s80, s0, 3
	global_load_lds_dwordx4 v[4:5], off
	s_add_i32 m0, s14, 0x1c000
	v_lshl_add_u64 v[4:5], v[8:9], 0, s[10:11]
	global_load_lds_dwordx4 v[4:5], off
	v_lshl_add_u64 v[4:5], v[10:11], 0, s[10:11]
	s_add_i32 m0, s14, 0x1e000
	s_ashr_i32 s0, s16, 31
	global_load_lds_dwordx4 v[4:5], off
	v_bfe_u32 v9, v20, 4, 2
	s_lshr_b32 s0, s0, 26
	v_and_b32_e32 v7, 15, v20
	s_add_i32 s0, s16, s0
	v_lshlrev_b32_e32 v6, 4, v9
	v_lshlrev_b32_e32 v8, 2, v20
	s_ashr_i32 s81, s0, 6
	v_lshl_or_b32 v17, s1, 6, v7
	v_lshl_or_b32 v7, v7, 6, v6
	s_lshl_b32 s0, s1, 13
	v_and_b32_e32 v8, 32, v8
	v_bitop3_b32 v12, v7, s0, v8 bitop3:0xde
	s_lshl_b32 s0, s80, 12
	s_cmp_gt_i32 s16, 63
	s_cselect_b64 s[68:69], -1, 0
	s_add_i32 s52, s81, -2
	s_cmpk_lt_u32 s17, 0x100
	s_cselect_b64 s[16:17], -1, 0
	s_lshl_b32 s57, s18, 4
	v_bitop3_b32 v234, v7, s0, v8 bitop3:0xde
	v_cvt_f32_u32_e32 v7, s57
	v_lshlrev_b32_e32 v0, 3, v9
	v_lshlrev_b32_e32 v8, 2, v9
	v_cmp_eq_u32_e64 s[82:83], 0, v9
	v_lshlrev_b32_e32 v10, 5, v9
	v_rcp_iflag_f32_e32 v9, v7
	s_lshr_b32 s0, s84, 3
	v_writelane_b32 v255, s0, 36
	s_add_i32 s99, s0, 1
	v_mul_f32_e32 v9, 0x4f7ffffe, v9
	v_cvt_u32_f32_e32 v9, v9
	v_readlane_b32 s0, v254, 50
	v_mov_b32_e32 v11, v1
	v_readlane_b32 s1, v254, 51
	v_mov_b32_e32 v7, v1
	s_waitcnt vmcnt(6)
	v_mov_b32_e32 v3, v2
	v_lshl_add_u64 v[188:189], s[0:1], 0, v[10:11]
	v_lshl_add_u64 v[190:191], s[0:1], 0, v[6:7]
	s_sub_i32 s0, 0, s57
	v_readfirstlane_b32 s1, v9
	s_mul_i32 s0, s0, s1
	s_mul_hi_u32 s0, s1, s0
	s_add_i32 s55, s1, s0
	v_readlane_b32 s0, v255, 22
	v_readlane_b32 s1, v255, 23
	v_mov_b32_e32 v4, v2
	v_mov_b32_e32 v5, v2
	v_lshl_add_u64 v[192:193], s[0:1], 0, v[0:1]
	v_readlane_b32 s0, v255, 24
	v_readlane_b32 s1, v255, 25
	v_or_b32_e32 v235, 16, v17
	v_or_b32_e32 v236, 32, v17
	v_lshl_add_u64 v[194:195], s[0:1], 0, v[6:7]
	v_add_u32_e32 v6, v23, v21
	v_add_lshl_u32 v6, v6, v22, 1
	v_lshl_add_u64 v[196:197], s[4:5], 0, v[6:7]
	v_add_u32_e32 v6, v26, v24
	v_add_lshl_u32 v6, v6, v25, 1
	v_or_b32_e32 v237, 48, v17
	v_add_u32_e32 v238, 0x90, v17
	v_add_u32_e32 v239, 0xa0, v17
	v_add_u32_e32 v240, 0xb0, v17
	s_mov_b32 s53, 0
	s_ashr_i32 s54, s70, 31
	s_mov_b32 s85, s91
	s_and_b32 s56, s84, 6
	v_lshl_or_b32 v241, s80, 5, v0
	v_lshl_add_u64 v[198:199], s[4:5], 0, v[6:7]
	v_add_u32_e32 v242, 0, v12
	v_lshlrev_b32_e32 v200, 1, v0
	v_lshlrev_b32_e32 v202, 1, v8
	s_barrier
	s_branch .LBB0_261

;     __device__ bool next(int i, Unit& u) const {
;         const long L = (long)i * G + c; if (L >= nwg) return false;
;         int wgid = (int)L; { const int q = nwg / NXCD, r = nwg % NXCD, xcd = wgid % NXCD, off = wgid / NXCD; wgid = (xcd < r ? xcd * (q + 1) : r * (q + 1) + (xcd - r) * q) + off; }
;         const int nig = WGM * nN, gid = wgid / nig, fm = gid * WGM, gsz = (nM - fm) < WGM ? (nM - fm) : WGM;
;         u.pm = fm + ((wgid % nig) % gsz); u.pn = (wgid % nig) / gsz; return true;
;     }
.LBB0_266:
	s_ashr_i32 s5, s5, 3
	s_add_i32 s5, s21, s5
	s_abs_i32 s19, s5
	s_mul_hi_u32 s20, s19, s55
	s_mul_i32 s21, s20, s57
	s_sub_i32 s19, s19, s21
	s_ashr_i32 s18, s5, 31
	s_add_i32 s21, s20, 1
	s_sub_i32 s22, s19, s57
	s_cmp_ge_u32 s19, s57
	s_cselect_b32 s20, s21, s20
	s_cselect_b32 s19, s22, s19
	s_add_i32 s21, s20, 1
	s_cmp_ge_u32 s19, s57
	s_cselect_b32 s19, s21, s20
	s_xor_b32 s19, s19, s18
	s_sub_i32 s18, s19, s18
	s_lshl_b32 s19, s18, 4
	s_sub_i32 s20, s96, s19
	s_min_i32 s20, s20, 16
	s_abs_i32 s21, s20
	v_cvt_f32_u32_e32 v0, s21
	s_sub_i32 s23, 0, s21
	s_mul_i32 s18, s18, s57
	s_sub_i32 s18, s5, s18
	v_rcp_iflag_f32_e32 v0, v0
	s_abs_i32 s5, s18
	s_xor_b32 s22, s18, s20
	s_ashr_i32 s22, s22, 31
	v_mul_f32_e32 v0, 0x4f7ffffe, v0
	v_cvt_u32_f32_e32 v0, v0
	s_nop 0
	v_readfirstlane_b32 s38, v0
	s_mul_i32 s23, s23, s38
	s_mul_hi_u32 s23, s38, s23
	s_add_i32 s38, s38, s23
	s_mul_hi_u32 s23, s5, s38
	s_mul_i32 s38, s23, s21
	s_sub_i32 s5, s5, s38
	s_add_i32 s38, s23, 1
	s_sub_i32 s39, s5, s21
	s_cmp_ge_u32 s5, s21
	s_cselect_b32 s23, s38, s23
	s_cselect_b32 s5, s39, s5
	s_add_i32 s38, s23, 1
	s_cmp_ge_u32 s5, s21
	s_cselect_b32 s5, s38, s23
	s_xor_b32 s5, s5, s22
	s_sub_i32 s5, s5, s22
	s_mul_i32 s20, s5, s20
	s_sub_i32 s18, s18, s20
	s_add_i32 s62, s18, s19
